# s27 + p3_gate_nt: P3 gate-image loads non-temporal
# baseline (speedup 1.0000x reference)
.LBB0_408:
	s_add_i32 s4, s62, 0x200
	s_ashr_i32 s5, s4, 31
	s_lshl_b64 s[4:5], s[4:5], 16
	v_lshl_add_u64 v[2:3], v[208:209], 0, s[4:5]
	global_load_dwordx4 v[132:135], v[2:3], off nt
	global_load_dwordx4 v[136:139], v[2:3], off offset:1024 nt
	v_pk_mul_f32 v[140:141], v[106:107], s[16:17] op_sel_hi:[1,0]
	v_pk_mul_f32 v[142:143], v[104:105], s[16:17] op_sel_hi:[1,0]
	global_load_dwordx4 v[104:107], v[2:3], off offset:2048 nt
	v_pk_mul_f32 v[144:145], v[102:103], s[16:17] op_sel_hi:[1,0]
	v_pk_mul_f32 v[146:147], v[100:101], s[16:17] op_sel_hi:[1,0]
	global_load_dwordx4 v[100:103], v[2:3], off offset:3072 nt
	s_lshl_b32 s4, s59, 9
	s_lshl_b32 s5, s28, 19
	v_pk_mul_f32 v[130:131], v[130:131], s[16:17] op_sel_hi:[1,0]
	v_pk_mul_f32 v[128:129], v[128:129], s[16:17] op_sel_hi:[1,0]
	v_pk_mul_f32 v[126:127], v[126:127], s[16:17] op_sel_hi:[1,0]
	v_pk_mul_f32 v[124:125], v[124:125], s[16:17] op_sel_hi:[1,0]
	v_pk_mul_f32 v[122:123], v[122:123], s[16:17] op_sel_hi:[1,0]
	v_pk_mul_f32 v[120:121], v[120:121], s[16:17] op_sel_hi:[1,0]
	v_pk_mul_f32 v[118:119], v[118:119], s[16:17] op_sel_hi:[1,0]
	v_pk_mul_f32 v[116:117], v[116:117], s[16:17] op_sel_hi:[1,0]
	v_pk_mul_f32 v[114:115], v[114:115], s[16:17] op_sel_hi:[1,0]
	v_pk_mul_f32 v[112:113], v[112:113], s[16:17] op_sel_hi:[1,0]
	v_pk_mul_f32 v[110:111], v[110:111], s[16:17] op_sel_hi:[1,0]
	v_pk_mul_f32 v[108:109], v[108:109], s[16:17] op_sel_hi:[1,0]
	s_add_i32 s5, s5, s4
	v_add_u32_e32 v0, s5, v218
	v_add_u32_e32 v170, 0x8000, v0
	v_pk_mul_f32 v[96:97], v[96:97], s[16:17] op_sel_hi:[1,0]
	v_pk_mul_f32 v[98:99], v[98:99], s[16:17] op_sel_hi:[1,0]
	v_pk_mul_f32 v[88:89], v[88:89], s[16:17] op_sel_hi:[1,0]
	v_pk_mul_f32 v[90:91], v[90:91], s[16:17] op_sel_hi:[1,0]
	v_pk_mul_f32 v[80:81], v[80:81], s[16:17] op_sel_hi:[1,0]
	v_pk_mul_f32 v[82:83], v[82:83], s[16:17] op_sel_hi:[1,0]
	v_pk_mul_f32 v[72:73], v[72:73], s[16:17] op_sel_hi:[1,0]
	v_pk_mul_f32 v[74:75], v[74:75], s[16:17] op_sel_hi:[1,0]
	v_add_co_u32_e32 v2, vcc, s57, v2
	v_pk_mul_f32 v[64:65], v[64:65], s[16:17] op_sel_hi:[1,0]
	s_nop 0
	v_addc_co_u32_e32 v3, vcc, 0, v3, vcc
	global_load_dwordx4 v[224:227], v[2:3], off nt
	global_load_dwordx4 v[228:231], v[2:3], off offset:1024 nt
	global_load_dwordx4 v[232:235], v[2:3], off offset:2048 nt
	global_load_dwordx4 v[236:239], v[2:3], off offset:3072 nt
	v_pk_mul_f32 v[56:57], v[56:57], s[16:17] op_sel_hi:[1,0]
	v_pk_mul_f32 v[48:49], v[48:49], s[16:17] op_sel_hi:[1,0]
	v_pk_mul_f32 v[40:41], v[40:41], s[16:17] op_sel_hi:[1,0]
	v_pk_mul_f32 v[32:33], v[32:33], s[16:17] op_sel_hi:[1,0]
	v_pk_mul_f32 v[24:25], v[24:25], s[16:17] op_sel_hi:[1,0]
	v_pk_mul_f32 v[16:17], v[16:17], s[16:17] op_sel_hi:[1,0]
	v_pk_mul_f32 v[10:11], v[10:11], s[16:17] op_sel_hi:[1,0]
	v_pk_mul_f32 v[4:5], v[4:5], s[16:17] op_sel_hi:[1,0]
	v_pk_mul_f32 v[6:7], v[6:7], s[16:17] op_sel_hi:[1,0]
	s_and_b64 vcc, exec, s[0:1]
	s_mov_b32 s59, s18
	s_mov_b32 s28, s20
	s_mov_b64 s[36:37], s[26:27]
	s_mov_b64 s[30:31], s[24:25]
	s_mov_b64 s[34:35], s[22:23]
	s_waitcnt vmcnt(4)
	v_cvt_f32_ubyte1_e32 v149, v132
	v_cvt_f32_ubyte0_e32 v148, v132
	v_cvt_f32_ubyte3_e32 v151, v132
	v_cvt_f32_ubyte2_e32 v150, v132
	v_cvt_f32_ubyte1_e32 v153, v133
	v_cvt_f32_ubyte0_e32 v152, v133
	v_cvt_f32_ubyte3_e32 v155, v133
	v_cvt_f32_ubyte2_e32 v154, v133
	v_cvt_f32_ubyte1_e32 v133, v134
	v_cvt_f32_ubyte0_e32 v132, v134
	v_cvt_f32_ubyte3_e32 v157, v134
	v_cvt_f32_ubyte2_e32 v156, v134
	v_cvt_f32_ubyte1_e32 v159, v135
	v_cvt_f32_ubyte0_e32 v158, v135
	v_cvt_f32_ubyte3_e32 v161, v135
	v_cvt_f32_ubyte2_e32 v160, v135
	v_cvt_f32_ubyte1_e32 v135, v136
	v_cvt_f32_ubyte0_e32 v134, v136
	v_cvt_f32_ubyte3_e32 v163, v136
	v_cvt_f32_ubyte2_e32 v162, v136
	v_cvt_f32_ubyte1_e32 v165, v137
	v_cvt_f32_ubyte0_e32 v164, v137
	v_cvt_f32_ubyte3_e32 v167, v137
	v_cvt_f32_ubyte2_e32 v166, v137
	v_pk_mul_f32 v[128:129], v[128:129], v[148:149]
	v_pk_mul_f32 v[130:131], v[130:131], v[150:151]
	v_pk_mul_f32 v[124:125], v[124:125], v[152:153]
	v_pk_mul_f32 v[126:127], v[126:127], v[154:155]
	v_pk_mul_f32 v[120:121], v[120:121], v[132:133]
	v_pk_mul_f32 v[122:123], v[122:123], v[156:157]
	v_pk_mul_f32 v[116:117], v[116:117], v[158:159]
	v_pk_mul_f32 v[118:119], v[118:119], v[160:161]
	v_pk_mul_f32 v[132:133], v[112:113], v[134:135]
	v_pk_mul_f32 v[134:135], v[114:115], v[162:163]
	v_pk_mul_f32 v[148:149], v[108:109], v[164:165]
	v_pk_mul_f32 v[150:151], v[110:111], v[166:167]
	v_cvt_pk_bf16_f32 v108, v128, v129
	v_cvt_pk_bf16_f32 v109, v130, v131
	v_cvt_pk_bf16_f32 v110, v124, v125
	v_cvt_pk_bf16_f32 v111, v126, v127
	v_cvt_pk_bf16_f32 v112, v120, v121
	v_cvt_pk_bf16_f32 v113, v122, v123
	v_cvt_pk_bf16_f32 v114, v116, v117
	v_cvt_pk_bf16_f32 v115, v118, v119
	v_cvt_pk_bf16_f32 v116, v132, v133
	v_cvt_pk_bf16_f32 v117, v134, v135
	v_cvt_pk_bf16_f32 v118, v148, v149
	v_cvt_pk_bf16_f32 v119, v150, v151
	buffer_store_dwordx4 v[108:111], v0, s[8:11], 0 offen
	buffer_store_dwordx4 v[112:115], v0, s[8:11], 0 offen offset:256
	buffer_store_dwordx4 v[116:119], v170, s[8:11], 0 offen
	v_cvt_f32_ubyte1_e32 v109, v139
	v_cvt_f32_ubyte0_e32 v108, v139
	v_pk_mul_f32 v[108:109], v[146:147], v[108:109]
	v_cvt_f32_ubyte1_e32 v137, v138
	v_cvt_pk_bf16_f32 v122, v108, v109
	v_cvt_f32_ubyte3_e32 v109, v139
	v_cvt_f32_ubyte2_e32 v108, v139
	v_pk_mul_f32 v[108:109], v[144:145], v[108:109]
	v_cvt_f32_ubyte0_e32 v136, v138
	v_cvt_pk_bf16_f32 v123, v108, v109
	v_pk_mul_f32 v[108:109], v[94:95], s[16:17] op_sel_hi:[1,0]
	v_pk_mul_f32 v[94:95], v[92:93], s[16:17] op_sel_hi:[1,0]
	v_cvt_f32_ubyte1_e32 v93, v104
	v_cvt_f32_ubyte0_e32 v92, v104
	v_pk_mul_f32 v[92:93], v[96:97], v[92:93]
	v_cvt_f32_ubyte3_e32 v97, v104
	v_cvt_f32_ubyte2_e32 v96, v104
	v_pk_mul_f32 v[96:97], v[98:99], v[96:97]
	v_cvt_pk_bf16_f32 v92, v92, v93
	v_cvt_pk_bf16_f32 v93, v96, v97
	v_cvt_f32_ubyte1_e32 v97, v105
	v_cvt_f32_ubyte0_e32 v96, v105
	v_cvt_f32_ubyte3_e32 v169, v138
	v_cvt_f32_ubyte2_e32 v168, v138
	v_pk_mul_f32 v[94:95], v[94:95], v[96:97]
	v_cvt_f32_ubyte3_e32 v97, v105
	v_cvt_f32_ubyte2_e32 v96, v105
	v_pk_mul_f32 v[136:137], v[142:143], v[136:137]
	v_pk_mul_f32 v[140:141], v[140:141], v[168:169]
	v_pk_mul_f32 v[96:97], v[108:109], v[96:97]
	v_cvt_pk_bf16_f32 v120, v136, v137
	v_cvt_pk_bf16_f32 v121, v140, v141
	v_add_u32_e32 v110, 0x10000, v0
	v_cvt_pk_bf16_f32 v94, v94, v95
	v_cvt_pk_bf16_f32 v95, v96, v97
	buffer_store_dwordx4 v[120:123], v170, s[8:11], 0 offen offset:256
	buffer_store_dwordx4 v[92:95], v110, s[8:11], 0 offen
	s_nop 1
	v_pk_mul_f32 v[92:93], v[86:87], s[16:17] op_sel_hi:[1,0]
	v_pk_mul_f32 v[86:87], v[84:85], s[16:17] op_sel_hi:[1,0]
	v_cvt_f32_ubyte1_e32 v85, v106
	v_cvt_f32_ubyte0_e32 v84, v106
	v_pk_mul_f32 v[84:85], v[88:89], v[84:85]
	v_cvt_f32_ubyte3_e32 v89, v106
	v_cvt_f32_ubyte2_e32 v88, v106
	v_pk_mul_f32 v[88:89], v[90:91], v[88:89]
	v_cvt_pk_bf16_f32 v84, v84, v85
	v_cvt_pk_bf16_f32 v85, v88, v89
	v_cvt_f32_ubyte1_e32 v89, v107
	v_cvt_f32_ubyte0_e32 v88, v107
	v_pk_mul_f32 v[86:87], v[86:87], v[88:89]
	v_cvt_f32_ubyte3_e32 v89, v107
	v_cvt_f32_ubyte2_e32 v88, v107
	v_pk_mul_f32 v[88:89], v[92:93], v[88:89]
	v_cvt_pk_bf16_f32 v86, v86, v87
	v_cvt_pk_bf16_f32 v87, v88, v89
	buffer_store_dwordx4 v[84:87], v110, s[8:11], 0 offen offset:256
	s_nop 1
	v_pk_mul_f32 v[84:85], v[78:79], s[16:17] op_sel_hi:[1,0]
	v_pk_mul_f32 v[78:79], v[76:77], s[16:17] op_sel_hi:[1,0]
	v_cvt_f32_ubyte1_e32 v77, v100
	v_cvt_f32_ubyte0_e32 v76, v100
	v_pk_mul_f32 v[76:77], v[80:81], v[76:77]
	v_cvt_f32_ubyte3_e32 v81, v100
	v_cvt_f32_ubyte2_e32 v80, v100
	v_pk_mul_f32 v[80:81], v[82:83], v[80:81]
	v_cvt_pk_bf16_f32 v76, v76, v77
	v_cvt_pk_bf16_f32 v77, v80, v81
	v_cvt_f32_ubyte1_e32 v81, v101
	v_cvt_f32_ubyte0_e32 v80, v101
	v_pk_mul_f32 v[78:79], v[78:79], v[80:81]
	v_cvt_f32_ubyte3_e32 v81, v101
	v_cvt_f32_ubyte2_e32 v80, v101
	v_pk_mul_f32 v[80:81], v[84:85], v[80:81]
	v_add_u32_e32 v86, 0x18000, v0
	v_cvt_pk_bf16_f32 v78, v78, v79
	v_cvt_pk_bf16_f32 v79, v80, v81
	buffer_store_dwordx4 v[76:79], v86, s[8:11], 0 offen
	v_add_u32_e32 v84, 0x40000, v0
	s_nop 0
	v_pk_mul_f32 v[76:77], v[70:71], s[16:17] op_sel_hi:[1,0]
	v_pk_mul_f32 v[70:71], v[68:69], s[16:17] op_sel_hi:[1,0]
	v_cvt_f32_ubyte1_e32 v69, v102
	v_cvt_f32_ubyte0_e32 v68, v102
	v_pk_mul_f32 v[68:69], v[72:73], v[68:69]
	v_cvt_f32_ubyte3_e32 v73, v102
	v_cvt_f32_ubyte2_e32 v72, v102
	v_pk_mul_f32 v[72:73], v[74:75], v[72:73]
	v_cvt_pk_bf16_f32 v68, v68, v69
	v_cvt_pk_bf16_f32 v69, v72, v73
	v_cvt_f32_ubyte1_e32 v73, v103
	v_cvt_f32_ubyte0_e32 v72, v103
	v_pk_mul_f32 v[70:71], v[70:71], v[72:73]
	v_cvt_f32_ubyte3_e32 v73, v103
	v_cvt_f32_ubyte2_e32 v72, v103
	v_pk_mul_f32 v[72:73], v[76:77], v[72:73]
	v_cvt_pk_bf16_f32 v70, v70, v71
	v_cvt_pk_bf16_f32 v71, v72, v73
	buffer_store_dwordx4 v[68:71], v86, s[8:11], 0 offen offset:256
	s_nop 0
	s_nop 0
	s_nop 0
	s_nop 0
	v_pk_mul_f32 v[2:3], v[66:67], s[16:17] op_sel_hi:[1,0]
	v_pk_mul_f32 v[66:67], v[62:63], s[16:17] op_sel_hi:[1,0]
	v_pk_mul_f32 v[62:63], v[60:61], s[16:17] op_sel_hi:[1,0]
	s_waitcnt vmcnt(8)
	v_cvt_f32_ubyte1_e32 v61, v224
	v_cvt_f32_ubyte0_e32 v60, v224
	v_pk_mul_f32 v[60:61], v[64:65], v[60:61]
	v_cvt_f32_ubyte3_e32 v65, v224
	v_cvt_f32_ubyte2_e32 v64, v224
	v_pk_mul_f32 v[2:3], v[2:3], v[64:65]
	v_cvt_pk_bf16_f32 v60, v60, v61
	v_cvt_pk_bf16_f32 v61, v2, v3
	v_cvt_f32_ubyte1_e32 v3, v225
	v_cvt_f32_ubyte0_e32 v2, v225
	v_pk_mul_f32 v[2:3], v[62:63], v[2:3]
	s_nop 0
	v_cvt_pk_bf16_f32 v62, v2, v3
	v_cvt_f32_ubyte3_e32 v3, v225
	v_cvt_f32_ubyte2_e32 v2, v225
	v_pk_mul_f32 v[2:3], v[66:67], v[2:3]
	s_nop 0
	v_cvt_pk_bf16_f32 v63, v2, v3
	v_pk_mul_f32 v[2:3], v[58:59], s[16:17] op_sel_hi:[1,0]
	v_pk_mul_f32 v[58:59], v[54:55], s[16:17] op_sel_hi:[1,0]
	v_pk_mul_f32 v[54:55], v[52:53], s[16:17] op_sel_hi:[1,0]
	v_cvt_f32_ubyte1_e32 v53, v226
	v_cvt_f32_ubyte0_e32 v52, v226
	v_pk_mul_f32 v[52:53], v[56:57], v[52:53]
	v_cvt_f32_ubyte3_e32 v57, v226
	v_cvt_f32_ubyte2_e32 v56, v226
	v_pk_mul_f32 v[2:3], v[2:3], v[56:57]
	v_cvt_pk_bf16_f32 v52, v52, v53
	v_cvt_pk_bf16_f32 v53, v2, v3
	v_cvt_f32_ubyte1_e32 v3, v227
	v_cvt_f32_ubyte0_e32 v2, v227
	v_pk_mul_f32 v[2:3], v[54:55], v[2:3]
	buffer_store_dwordx4 v[60:63], v84, s[8:11], 0 offen
	v_cvt_pk_bf16_f32 v54, v2, v3
	v_cvt_f32_ubyte3_e32 v3, v227
	v_cvt_f32_ubyte2_e32 v2, v227
	v_pk_mul_f32 v[2:3], v[58:59], v[2:3]
	s_nop 0
	v_cvt_pk_bf16_f32 v55, v2, v3
	v_pk_mul_f32 v[2:3], v[50:51], s[16:17] op_sel_hi:[1,0]
	v_pk_mul_f32 v[50:51], v[46:47], s[16:17] op_sel_hi:[1,0]
	v_pk_mul_f32 v[46:47], v[44:45], s[16:17] op_sel_hi:[1,0]
	s_nop 0
	v_cvt_f32_ubyte1_e32 v45, v228
	v_cvt_f32_ubyte0_e32 v44, v228
	v_pk_mul_f32 v[44:45], v[48:49], v[44:45]
	v_cvt_f32_ubyte3_e32 v49, v228
	v_cvt_f32_ubyte2_e32 v48, v228
	v_pk_mul_f32 v[2:3], v[2:3], v[48:49]
	v_cvt_pk_bf16_f32 v44, v44, v45
	v_cvt_pk_bf16_f32 v45, v2, v3
	v_cvt_f32_ubyte1_e32 v3, v229
	v_cvt_f32_ubyte0_e32 v2, v229
	v_pk_mul_f32 v[2:3], v[46:47], v[2:3]
	buffer_store_dwordx4 v[52:55], v84, s[8:11], 0 offen offset:256
	v_cvt_pk_bf16_f32 v46, v2, v3
	v_cvt_f32_ubyte3_e32 v3, v229
	v_cvt_f32_ubyte2_e32 v2, v229
	v_pk_mul_f32 v[2:3], v[50:51], v[2:3]
	v_add_u32_e32 v52, 0x48000, v0
	v_cvt_pk_bf16_f32 v47, v2, v3
	v_pk_mul_f32 v[2:3], v[42:43], s[16:17] op_sel_hi:[1,0]
	v_pk_mul_f32 v[42:43], v[38:39], s[16:17] op_sel_hi:[1,0]
	v_pk_mul_f32 v[38:39], v[36:37], s[16:17] op_sel_hi:[1,0]
	v_cvt_f32_ubyte1_e32 v37, v230
	v_cvt_f32_ubyte0_e32 v36, v230
	v_pk_mul_f32 v[36:37], v[40:41], v[36:37]
	v_cvt_f32_ubyte3_e32 v41, v230
	v_cvt_f32_ubyte2_e32 v40, v230
	v_pk_mul_f32 v[2:3], v[2:3], v[40:41]
	v_cvt_pk_bf16_f32 v36, v36, v37
	v_cvt_pk_bf16_f32 v37, v2, v3
	v_cvt_f32_ubyte1_e32 v3, v231
	v_cvt_f32_ubyte0_e32 v2, v231
	v_pk_mul_f32 v[2:3], v[38:39], v[2:3]
	buffer_store_dwordx4 v[44:47], v52, s[8:11], 0 offen
	v_cvt_pk_bf16_f32 v38, v2, v3
	v_cvt_f32_ubyte3_e32 v3, v231
	v_cvt_f32_ubyte2_e32 v2, v231
	v_pk_mul_f32 v[2:3], v[42:43], v[2:3]
	s_nop 0
	v_cvt_pk_bf16_f32 v39, v2, v3
	v_pk_mul_f32 v[2:3], v[34:35], s[16:17] op_sel_hi:[1,0]
	v_pk_mul_f32 v[34:35], v[30:31], s[16:17] op_sel_hi:[1,0]
	v_pk_mul_f32 v[30:31], v[28:29], s[16:17] op_sel_hi:[1,0]
	s_nop 0
	v_cvt_f32_ubyte1_e32 v29, v232
	v_cvt_f32_ubyte0_e32 v28, v232
	v_pk_mul_f32 v[28:29], v[32:33], v[28:29]
	v_cvt_f32_ubyte3_e32 v33, v232
	v_cvt_f32_ubyte2_e32 v32, v232
	v_pk_mul_f32 v[2:3], v[2:3], v[32:33]
	v_cvt_pk_bf16_f32 v28, v28, v29
	v_cvt_pk_bf16_f32 v29, v2, v3
	v_cvt_f32_ubyte1_e32 v3, v233
	v_cvt_f32_ubyte0_e32 v2, v233
	v_pk_mul_f32 v[2:3], v[30:31], v[2:3]
	buffer_store_dwordx4 v[36:39], v52, s[8:11], 0 offen offset:256
	v_cvt_pk_bf16_f32 v30, v2, v3
	v_cvt_f32_ubyte3_e32 v3, v233
	v_cvt_f32_ubyte2_e32 v2, v233
	v_pk_mul_f32 v[2:3], v[34:35], v[2:3]
	v_add_u32_e32 v36, 0x50000, v0
	v_cvt_pk_bf16_f32 v31, v2, v3
	v_pk_mul_f32 v[2:3], v[26:27], s[16:17] op_sel_hi:[1,0]
	v_pk_mul_f32 v[26:27], v[22:23], s[16:17] op_sel_hi:[1,0]
	v_pk_mul_f32 v[22:23], v[20:21], s[16:17] op_sel_hi:[1,0]
	v_cvt_f32_ubyte1_e32 v21, v234
	v_cvt_f32_ubyte0_e32 v20, v234
	v_pk_mul_f32 v[20:21], v[24:25], v[20:21]
	v_cvt_f32_ubyte3_e32 v25, v234
	v_cvt_f32_ubyte2_e32 v24, v234
	v_pk_mul_f32 v[2:3], v[2:3], v[24:25]
	v_cvt_pk_bf16_f32 v20, v20, v21
	v_cvt_pk_bf16_f32 v21, v2, v3
	v_cvt_f32_ubyte1_e32 v3, v235
	v_cvt_f32_ubyte0_e32 v2, v235
	v_pk_mul_f32 v[2:3], v[22:23], v[2:3]
	v_add_u32_e32 v0, 0x58000, v0
	v_cvt_pk_bf16_f32 v22, v2, v3
	v_cvt_f32_ubyte3_e32 v3, v235
	v_cvt_f32_ubyte2_e32 v2, v235
	v_pk_mul_f32 v[2:3], v[26:27], v[2:3]
	buffer_store_dwordx4 v[28:31], v36, s[8:11], 0 offen
	v_cvt_pk_bf16_f32 v23, v2, v3
	v_pk_mul_f32 v[2:3], v[18:19], s[16:17] op_sel_hi:[1,0]
	v_pk_mul_f32 v[18:19], v[14:15], s[16:17] op_sel_hi:[1,0]
	v_pk_mul_f32 v[14:15], v[12:13], s[16:17] op_sel_hi:[1,0]
	s_nop 0
	v_cvt_f32_ubyte1_e32 v13, v236
	v_cvt_f32_ubyte0_e32 v12, v236
	v_pk_mul_f32 v[12:13], v[16:17], v[12:13]
	v_cvt_f32_ubyte3_e32 v17, v236
	v_cvt_f32_ubyte2_e32 v16, v236
	v_pk_mul_f32 v[2:3], v[2:3], v[16:17]
	v_cvt_pk_bf16_f32 v12, v12, v13
	v_cvt_pk_bf16_f32 v13, v2, v3
	v_cvt_f32_ubyte1_e32 v3, v237
	v_cvt_f32_ubyte0_e32 v2, v237
	v_pk_mul_f32 v[2:3], v[14:15], v[2:3]
	buffer_store_dwordx4 v[20:23], v36, s[8:11], 0 offen offset:256
	v_cvt_pk_bf16_f32 v14, v2, v3
	v_cvt_f32_ubyte3_e32 v3, v237
	v_cvt_f32_ubyte2_e32 v2, v237
	v_pk_mul_f32 v[2:3], v[18:19], v[2:3]
	s_nop 0
	v_cvt_pk_bf16_f32 v15, v2, v3
	v_pk_mul_f32 v[2:3], v[8:9], s[16:17] op_sel_hi:[1,0]
	v_cvt_f32_ubyte1_e32 v9, v238
	v_cvt_f32_ubyte0_e32 v8, v238
	v_pk_mul_f32 v[2:3], v[2:3], v[8:9]
	v_cvt_f32_ubyte3_e32 v9, v238
	v_cvt_f32_ubyte2_e32 v8, v238
	v_pk_mul_f32 v[8:9], v[10:11], v[8:9]
	v_cvt_pk_bf16_f32 v2, v2, v3
	v_cvt_pk_bf16_f32 v3, v8, v9
	v_cvt_f32_ubyte1_e32 v9, v239
	v_cvt_f32_ubyte0_e32 v8, v239
	v_pk_mul_f32 v[4:5], v[4:5], v[8:9]
	v_cvt_f32_ubyte3_e32 v9, v239
	v_cvt_f32_ubyte2_e32 v8, v239
	v_pk_mul_f32 v[6:7], v[6:7], v[8:9]
	v_cvt_pk_bf16_f32 v4, v4, v5
	v_cvt_pk_bf16_f32 v5, v6, v7
	buffer_store_dwordx4 v[12:15], v0, s[8:11], 0 offen
	buffer_store_dwordx4 v[2:5], v0, s[8:11], 0 offen offset:256
	s_cbranch_vccnz .LBB0_431

.LBB0_419:
	s_andn2_b64 vcc, exec, s[42:43]
	s_cbranch_vccnz .LBB0_421
	s_cmp_eq_u32 s64, 8
	s_movk_i32 s12, 0x100
	s_cselect_b32 s12, s12, 0x200
	s_cselect_b32 s42, 0, 0x100
	s_add_i32 s44, s12, s62
	s_ashr_i32 s45, s44, 31
	s_lshl_b64 s[44:45], s[44:45], 16
	v_lshl_add_u64 v[156:157], v[208:209], 0, s[44:45]
	global_load_dwordx4 v[158:161], v[156:157], off nt
	s_add_i32 s42, s42, s62
	s_ashr_i32 s43, s42, 31
	s_lshl_b64 s[42:43], s[42:43], 16
	v_lshl_add_u64 v[2:3], v[208:209], 0, s[42:43]
	global_load_dwordx4 v[162:165], v[2:3], off nt
	global_load_dwordx4 v[152:155], v[156:157], off offset:1024 nt
	global_load_dwordx4 v[148:151], v[2:3], off offset:1024 nt
	global_load_dwordx4 v[140:143], v[2:3], off offset:2048 nt
	global_load_dwordx4 v[132:135], v[2:3], off offset:3072 nt
	global_load_dwordx4 v[144:147], v[156:157], off offset:2048 nt
	global_load_dwordx4 v[136:139], v[156:157], off offset:3072 nt
	s_add_u32 s44, s44, 0x1000
	s_addc_u32 s45, s45, 0
	s_add_u32 s42, s42, 0x1000
	s_addc_u32 s43, s43, 0
	v_lshl_add_u64 v[156:157], v[208:209], 0, s[44:45]
	v_lshl_add_u64 v[2:3], v[208:209], 0, s[42:43]
	global_load_dwordx4 v[222:225], v[156:157], off nt
	global_load_dwordx4 v[226:229], v[2:3], off nt
	global_load_dwordx4 v[230:233], v[2:3], off offset:1024 nt
	global_load_dwordx4 v[234:237], v[156:157], off offset:1024 nt
	global_load_dwordx4 v[238:241], v[2:3], off offset:2048 nt
	global_load_dwordx4 v[242:245], v[2:3], off offset:3072 nt
	global_load_dwordx4 v[246:249], v[156:157], off offset:2048 nt
	global_load_dwordx4 v[250:253], v[156:157], off offset:3072 nt
	s_waitcnt vmcnt(8)
	v_cvt_f32_ubyte3_e32 v167, v162
	v_cvt_f32_ubyte2_e32 v186, v160
	v_cvt_f32_ubyte3_e32 v187, v160
	v_rcp_iflag_f32_e32 v186, v186
	v_rcp_iflag_f32_e32 v187, v187
	v_cvt_f32_ubyte0_e32 v0, v158
	v_cvt_f32_ubyte1_e32 v177, v158
	v_cvt_f32_ubyte2_e32 v178, v158
	v_cvt_f32_ubyte3_e32 v179, v158
	v_cvt_f32_ubyte2_e32 v166, v162
	v_cvt_f32_ubyte1_e32 v169, v162
	v_cvt_f32_ubyte0_e32 v168, v162
	v_cvt_f32_ubyte0_e32 v180, v159
	v_cvt_f32_ubyte1_e32 v181, v159
	v_cvt_f32_ubyte2_e32 v182, v159
	v_cvt_f32_ubyte3_e32 v183, v159
	v_cvt_f32_ubyte3_e32 v159, v163
	v_cvt_f32_ubyte2_e32 v158, v163
	v_cvt_f32_ubyte1_e32 v171, v163
	v_cvt_f32_ubyte0_e32 v170, v163
	v_cvt_f32_ubyte3_e32 v163, v164
	v_cvt_f32_ubyte2_e32 v162, v164
	v_cvt_f32_ubyte2_e32 v190, v161
	v_cvt_f32_ubyte3_e32 v191, v161
	v_rcp_iflag_f32_e32 v176, v0
	v_rcp_iflag_f32_e32 v178, v178
	v_rcp_iflag_f32_e32 v179, v179
	v_pk_mul_f32 v[162:163], v[186:187], v[162:163]
	v_cvt_f32_ubyte0_e32 v0, v153
	v_cvt_f32_ubyte0_e32 v192, v152
	v_cvt_f32_ubyte1_e32 v193, v152
	v_cvt_f32_ubyte2_e32 v194, v152
	v_cvt_f32_ubyte3_e32 v152, v152
	v_rcp_iflag_f32_e32 v182, v182
	v_rcp_iflag_f32_e32 v183, v183
	v_rcp_iflag_f32_e32 v190, v190
	v_rcp_iflag_f32_e32 v191, v191
	v_pk_mul_f32 v[122:123], v[122:123], v[162:163]
	v_rcp_iflag_f32_e32 v162, v0
	v_cvt_f32_ubyte1_e32 v0, v153
	v_rcp_iflag_f32_e32 v194, v194
	v_rcp_iflag_f32_e32 v195, v152
	v_rcp_iflag_f32_e32 v163, v0
	v_cvt_f32_ubyte2_e32 v0, v153
	v_rcp_iflag_f32_e32 v152, v0
	v_cvt_f32_ubyte3_e32 v0, v153
	v_cvt_f32_ubyte0_e32 v184, v160
	v_cvt_f32_ubyte1_e32 v185, v160
	v_cvt_f32_ubyte0_e32 v188, v161
	v_cvt_f32_ubyte1_e32 v189, v161
	v_cvt_f32_ubyte3_e32 v161, v165
	v_cvt_f32_ubyte2_e32 v160, v165
	v_pk_mul_f32 v[166:167], v[178:179], v[166:167]
	v_rcp_iflag_f32_e32 v153, v0
	v_cvt_f32_ubyte1_e32 v173, v164
	v_cvt_f32_ubyte0_e32 v172, v164
	v_cvt_f32_ubyte1_e32 v175, v165
	v_cvt_f32_ubyte0_e32 v174, v165
	v_cvt_f32_ubyte3_e32 v165, v148
	v_cvt_f32_ubyte2_e32 v164, v148
	v_pk_mul_f32 v[158:159], v[182:183], v[158:159]
	v_pk_mul_f32 v[160:161], v[190:191], v[160:161]
	v_pk_mul_f32 v[130:131], v[130:131], v[166:167]
	v_cvt_f32_ubyte1_e32 v167, v149
	v_cvt_f32_ubyte0_e32 v166, v149
	v_pk_mul_f32 v[126:127], v[126:127], v[158:159]
	v_pk_mul_f32 v[118:119], v[118:119], v[160:161]
	v_cvt_f32_ubyte1_e32 v159, v148
	v_cvt_f32_ubyte0_e32 v158, v148
	v_pk_mul_f32 v[160:161], v[194:195], v[164:165]
	v_cvt_f32_ubyte3_e32 v165, v149
	v_cvt_f32_ubyte2_e32 v164, v149
	v_pk_mul_f32 v[148:149], v[162:163], v[166:167]
	v_cvt_f32_ubyte0_e32 v0, v154
	v_pk_mul_f32 v[108:109], v[108:109], v[148:149]
	v_rcp_iflag_f32_e32 v148, v0
	v_cvt_f32_ubyte1_e32 v0, v154
	v_rcp_iflag_f32_e32 v192, v192
	v_rcp_iflag_f32_e32 v193, v193
	v_pk_mul_f32 v[152:153], v[152:153], v[164:165]
	v_rcp_iflag_f32_e32 v149, v0
	v_cvt_f32_ubyte2_e32 v0, v154
	v_pk_mul_f32 v[110:111], v[110:111], v[152:153]
	v_rcp_iflag_f32_e32 v152, v0
	v_cvt_f32_ubyte3_e32 v0, v154
	v_rcp_iflag_f32_e32 v153, v0
	v_pk_mul_f32 v[158:159], v[192:193], v[158:159]
	v_cvt_f32_ubyte0_e32 v0, v155
	v_pk_mul_f32 v[112:113], v[112:113], v[158:159]
	v_cvt_f32_ubyte3_e32 v159, v150
	v_cvt_f32_ubyte2_e32 v158, v150
	v_pk_mul_f32 v[152:153], v[152:153], v[158:159]
	v_rcp_iflag_f32_e32 v158, v0
	v_cvt_f32_ubyte1_e32 v0, v155
	v_rcp_iflag_f32_e32 v159, v0
	v_cvt_f32_ubyte2_e32 v0, v155
	v_pk_mul_f32 v[114:115], v[114:115], v[160:161]
	v_cvt_f32_ubyte1_e32 v161, v150
	v_cvt_f32_ubyte0_e32 v160, v150
	v_rcp_iflag_f32_e32 v154, v0
	v_cvt_f32_ubyte3_e32 v0, v155
	v_pk_mul_f32 v[148:149], v[148:149], v[160:161]
	v_rcp_iflag_f32_e32 v155, v0
	v_cvt_f32_ubyte0_e32 v0, v144
	v_cvt_f32_ubyte1_e32 v163, v151
	v_cvt_f32_ubyte0_e32 v162, v151
	v_pk_mul_f32 v[104:105], v[104:105], v[148:149]
	v_rcp_iflag_f32_e32 v148, v0
	v_cvt_f32_ubyte1_e32 v0, v144
	v_cvt_f32_ubyte3_e32 v161, v151
	v_cvt_f32_ubyte2_e32 v160, v151
	v_pk_mul_f32 v[150:151], v[158:159], v[162:163]
	v_rcp_iflag_f32_e32 v149, v0
	v_cvt_f32_ubyte2_e32 v0, v144
	v_pk_mul_f32 v[100:101], v[100:101], v[150:151]
	v_rcp_iflag_f32_e32 v150, v0
	v_cvt_f32_ubyte3_e32 v0, v144
	v_rcp_iflag_f32_e32 v151, v0
	v_pk_mul_f32 v[106:107], v[106:107], v[152:153]
	v_cvt_f32_ubyte3_e32 v153, v140
	v_cvt_f32_ubyte2_e32 v152, v140
	v_cvt_f32_ubyte0_e32 v0, v145
	v_pk_mul_f32 v[150:151], v[150:151], v[152:153]
	v_rcp_iflag_f32_e32 v152, v0
	v_cvt_f32_ubyte1_e32 v0, v145
	v_rcp_iflag_f32_e32 v153, v0
	v_cvt_f32_ubyte2_e32 v0, v145
	v_rcp_iflag_f32_e32 v144, v0
	v_cvt_f32_ubyte3_e32 v0, v145
	v_pk_mul_f32 v[154:155], v[154:155], v[160:161]
	v_rcp_iflag_f32_e32 v145, v0
	v_pk_mul_f32 v[102:103], v[102:103], v[154:155]
	v_cvt_f32_ubyte1_e32 v155, v140
	v_cvt_f32_ubyte0_e32 v154, v140
	v_cvt_f32_ubyte1_e32 v159, v141
	v_cvt_f32_ubyte0_e32 v158, v141
	v_pk_mul_f32 v[148:149], v[148:149], v[154:155]
	v_cvt_f32_ubyte3_e32 v155, v141
	v_cvt_f32_ubyte2_e32 v154, v141
	v_pk_mul_f32 v[140:141], v[152:153], v[158:159]
	v_cvt_f32_ubyte0_e32 v0, v146
	v_pk_mul_f32 v[92:93], v[92:93], v[140:141]
	v_rcp_iflag_f32_e32 v140, v0
	v_cvt_f32_ubyte1_e32 v0, v146
	v_pk_mul_f32 v[144:145], v[144:145], v[154:155]
	v_rcp_iflag_f32_e32 v141, v0
	v_cvt_f32_ubyte2_e32 v0, v146
	v_pk_mul_f32 v[94:95], v[94:95], v[144:145]
	v_rcp_iflag_f32_e32 v144, v0
	v_cvt_f32_ubyte3_e32 v0, v146
	v_rcp_iflag_f32_e32 v145, v0
	v_pk_mul_f32 v[96:97], v[96:97], v[148:149]
	v_cvt_f32_ubyte3_e32 v149, v142
	v_cvt_f32_ubyte2_e32 v148, v142
	v_cvt_f32_ubyte0_e32 v0, v147
	v_pk_mul_f32 v[144:145], v[144:145], v[148:149]
	v_rcp_iflag_f32_e32 v148, v0
	v_cvt_f32_ubyte1_e32 v0, v147
	v_rcp_iflag_f32_e32 v149, v0
	v_cvt_f32_ubyte2_e32 v0, v147
	v_rcp_iflag_f32_e32 v146, v0
	v_cvt_f32_ubyte3_e32 v0, v147
	v_rcp_iflag_f32_e32 v147, v0
	v_pk_mul_f32 v[98:99], v[98:99], v[150:151]
	v_cvt_f32_ubyte1_e32 v151, v142
	v_cvt_f32_ubyte0_e32 v150, v142
	s_nop 0
	v_pk_mul_f32 v[140:141], v[140:141], v[150:151]
	v_cvt_f32_ubyte3_e32 v151, v143
	v_cvt_f32_ubyte2_e32 v150, v143
	v_cvt_f32_ubyte1_e32 v153, v143
	v_cvt_f32_ubyte0_e32 v152, v143
	s_nop 0
	v_pk_mul_f32 v[142:143], v[148:149], v[152:153]
	v_pk_mul_f32 v[146:147], v[146:147], v[150:151]
	s_nop 0
	s_nop 0
	v_cvt_f32_ubyte0_e32 v0, v136
	s_nop 0
	s_nop 0
	s_nop 0
	s_nop 0
	v_pk_mul_f32 v[88:89], v[88:89], v[140:141]
	v_rcp_iflag_f32_e32 v140, v0
	v_cvt_f32_ubyte1_e32 v0, v136
	v_rcp_iflag_f32_e32 v141, v0
	v_cvt_f32_ubyte2_e32 v0, v136
	v_pk_mul_f32 v[84:85], v[84:85], v[142:143]
	v_rcp_iflag_f32_e32 v142, v0
	v_cvt_f32_ubyte3_e32 v0, v136
	v_rcp_iflag_f32_e32 v143, v0
	v_pk_mul_f32 v[90:91], v[90:91], v[144:145]
	v_cvt_f32_ubyte3_e32 v145, v132
	v_cvt_f32_ubyte2_e32 v144, v132
	v_cvt_f32_ubyte0_e32 v0, v137
	v_pk_mul_f32 v[142:143], v[142:143], v[144:145]
	v_rcp_iflag_f32_e32 v144, v0
	v_cvt_f32_ubyte1_e32 v0, v137
	v_rcp_iflag_f32_e32 v145, v0
	v_pk_mul_f32 v[86:87], v[86:87], v[146:147]
	v_cvt_f32_ubyte1_e32 v147, v132
	v_cvt_f32_ubyte0_e32 v146, v132
	v_cvt_f32_ubyte1_e32 v157, v133
	v_cvt_f32_ubyte0_e32 v156, v133
	v_pk_mul_f32 v[140:141], v[140:141], v[146:147]
	v_cvt_f32_ubyte3_e32 v147, v133
	v_cvt_f32_ubyte2_e32 v146, v133
	v_pk_mul_f32 v[132:133], v[144:145], v[156:157]
	s_nop 0
	v_cvt_f32_ubyte2_e32 v0, v137
	v_rcp_iflag_f32_e32 v136, v0
	v_cvt_f32_ubyte3_e32 v0, v137
	v_rcp_iflag_f32_e32 v137, v0
	v_cvt_f32_ubyte0_e32 v0, v138
	v_pk_mul_f32 v[76:77], v[76:77], v[132:133]
	v_rcp_iflag_f32_e32 v132, v0
	v_cvt_f32_ubyte1_e32 v0, v138
	v_pk_mul_f32 v[136:137], v[136:137], v[146:147]
	v_rcp_iflag_f32_e32 v133, v0
	v_cvt_f32_ubyte2_e32 v0, v138
	v_pk_mul_f32 v[78:79], v[78:79], v[136:137]
	v_rcp_iflag_f32_e32 v136, v0
	v_cvt_f32_ubyte3_e32 v0, v138
	v_rcp_iflag_f32_e32 v137, v0
	v_pk_mul_f32 v[80:81], v[80:81], v[140:141]
	v_cvt_f32_ubyte3_e32 v141, v134
	v_cvt_f32_ubyte2_e32 v140, v134
	v_cvt_f32_ubyte0_e32 v0, v139
	v_pk_mul_f32 v[136:137], v[136:137], v[140:141]
	v_rcp_iflag_f32_e32 v140, v0
	v_cvt_f32_ubyte1_e32 v0, v139
	v_rcp_iflag_f32_e32 v141, v0
	v_cvt_f32_ubyte2_e32 v0, v139
	v_rcp_iflag_f32_e32 v138, v0
	v_cvt_f32_ubyte3_e32 v0, v139
	v_rcp_iflag_f32_e32 v139, v0
	v_pk_mul_f32 v[82:83], v[82:83], v[142:143]
	v_cvt_f32_ubyte1_e32 v143, v134
	v_cvt_f32_ubyte0_e32 v142, v134
	v_pk_mul_f32 v[132:133], v[132:133], v[142:143]
	v_cvt_f32_ubyte3_e32 v143, v135
	v_cvt_f32_ubyte2_e32 v142, v135
	v_cvt_f32_ubyte1_e32 v145, v135
	v_cvt_f32_ubyte0_e32 v144, v135
	v_pk_mul_f32 v[134:135], v[140:141], v[144:145]
	v_pk_mul_f32 v[138:139], v[138:139], v[142:143]
	v_pk_mul_f32 v[74:75], v[74:75], v[136:137]
	v_pk_mul_f32 v[72:73], v[72:73], v[132:133]
	v_pk_mul_f32 v[70:71], v[70:71], v[138:139]
	v_pk_mul_f32 v[68:69], v[68:69], v[134:135]
	s_nop 0
	s_nop 0
	s_nop 0
	s_nop 0
	v_rcp_iflag_f32_e32 v177, v177
	v_rcp_iflag_f32_e32 v180, v180
	v_rcp_iflag_f32_e32 v181, v181
	s_waitcnt vmcnt(0)
	v_cvt_f32_ubyte0_e32 v0, v222
	v_rcp_iflag_f32_e32 v2, v0
	v_cvt_f32_ubyte1_e32 v0, v222
	v_rcp_iflag_f32_e32 v3, v0
	v_cvt_f32_ubyte2_e32 v0, v222
	v_rcp_iflag_f32_e32 v164, v0
	v_cvt_f32_ubyte3_e32 v0, v222
	v_rcp_iflag_f32_e32 v165, v0
	v_cvt_f32_ubyte3_e32 v167, v226
	v_cvt_f32_ubyte2_e32 v166, v226
	v_cvt_f32_ubyte0_e32 v0, v223
	v_pk_mul_f32 v[164:165], v[164:165], v[166:167]
	v_rcp_iflag_f32_e32 v166, v0
	v_cvt_f32_ubyte1_e32 v0, v223
	v_rcp_iflag_f32_e32 v167, v0
	v_cvt_f32_ubyte2_e32 v0, v223
	v_rcp_iflag_f32_e32 v148, v0
	v_cvt_f32_ubyte3_e32 v0, v223
	v_pk_mul_f32 v[168:169], v[176:177], v[168:169]
	v_rcp_iflag_f32_e32 v149, v0
	v_pk_mul_f32 v[128:129], v[128:129], v[168:169]
	v_cvt_f32_ubyte1_e32 v169, v226
	v_cvt_f32_ubyte0_e32 v168, v226
	v_pk_mul_f32 v[2:3], v[2:3], v[168:169]
	v_cvt_f32_ubyte0_e32 v0, v224
	v_cvt_f32_ubyte3_e32 v169, v227
	v_cvt_f32_ubyte2_e32 v168, v227
	v_pk_mul_f32 v[64:65], v[64:65], v[2:3]
	v_rcp_iflag_f32_e32 v2, v0
	v_cvt_f32_ubyte1_e32 v0, v224
	v_pk_mul_f32 v[148:149], v[148:149], v[168:169]
	v_rcp_iflag_f32_e32 v3, v0
	v_cvt_f32_ubyte2_e32 v0, v224
	v_pk_mul_f32 v[62:63], v[62:63], v[148:149]
	v_rcp_iflag_f32_e32 v148, v0
	v_cvt_f32_ubyte3_e32 v0, v224
	v_pk_mul_f32 v[170:171], v[180:181], v[170:171]
	v_rcp_iflag_f32_e32 v149, v0
	v_pk_mul_f32 v[124:125], v[124:125], v[170:171]
	v_cvt_f32_ubyte1_e32 v171, v227
	v_cvt_f32_ubyte0_e32 v170, v227
	v_pk_mul_f32 v[152:153], v[166:167], v[170:171]
	v_cvt_f32_ubyte0_e32 v0, v225
	v_pk_mul_f32 v[60:61], v[60:61], v[152:153]
	v_cvt_f32_ubyte3_e32 v153, v228
	v_cvt_f32_ubyte2_e32 v152, v228
	v_pk_mul_f32 v[148:149], v[148:149], v[152:153]
	v_rcp_iflag_f32_e32 v152, v0
	v_cvt_f32_ubyte1_e32 v0, v225
	v_rcp_iflag_f32_e32 v153, v0
	v_cvt_f32_ubyte2_e32 v0, v225
	v_pk_mul_f32 v[66:67], v[66:67], v[164:165]
	v_cvt_f32_ubyte1_e32 v165, v228
	v_cvt_f32_ubyte0_e32 v164, v228
	v_rcp_iflag_f32_e32 v150, v0
	v_cvt_f32_ubyte3_e32 v0, v225
	v_pk_mul_f32 v[2:3], v[2:3], v[164:165]
	v_rcp_iflag_f32_e32 v151, v0
	v_cvt_f32_ubyte0_e32 v0, v234
	v_pk_mul_f32 v[56:57], v[56:57], v[2:3]
	v_rcp_iflag_f32_e32 v2, v0
	v_cvt_f32_ubyte1_e32 v0, v234
	v_rcp_iflag_f32_e32 v3, v0
	v_cvt_f32_ubyte2_e32 v0, v234
	v_pk_mul_f32 v[58:59], v[58:59], v[148:149]
	v_rcp_iflag_f32_e32 v148, v0
	v_cvt_f32_ubyte3_e32 v0, v234
	v_rcp_iflag_f32_e32 v149, v0
	v_cvt_f32_ubyte3_e32 v165, v229
	v_cvt_f32_ubyte2_e32 v164, v229
	v_pk_mul_f32 v[150:151], v[150:151], v[164:165]
	v_cvt_f32_ubyte1_e32 v167, v229
	v_cvt_f32_ubyte0_e32 v166, v229
	v_pk_mul_f32 v[54:55], v[54:55], v[150:151]
	v_cvt_f32_ubyte3_e32 v151, v230
	v_cvt_f32_ubyte2_e32 v150, v230
	v_cvt_f32_ubyte0_e32 v0, v235
	v_pk_mul_f32 v[152:153], v[152:153], v[166:167]
	v_pk_mul_f32 v[148:149], v[148:149], v[150:151]
	v_rcp_iflag_f32_e32 v150, v0
	v_cvt_f32_ubyte1_e32 v0, v235
	v_pk_mul_f32 v[52:53], v[52:53], v[152:153]
	v_cvt_f32_ubyte1_e32 v153, v230
	v_cvt_f32_ubyte0_e32 v152, v230
	v_rcp_iflag_f32_e32 v151, v0
	v_cvt_f32_ubyte2_e32 v0, v235
	v_pk_mul_f32 v[2:3], v[2:3], v[152:153]
	v_rcp_iflag_f32_e32 v152, v0
	v_cvt_f32_ubyte3_e32 v0, v235
	v_rcp_iflag_f32_e32 v153, v0
	v_cvt_f32_ubyte0_e32 v0, v236
	v_pk_mul_f32 v[48:49], v[48:49], v[2:3]
	v_rcp_iflag_f32_e32 v2, v0
	v_cvt_f32_ubyte1_e32 v0, v236
	v_rcp_iflag_f32_e32 v3, v0
	v_cvt_f32_ubyte2_e32 v0, v236
	v_pk_mul_f32 v[50:51], v[50:51], v[148:149]
	v_rcp_iflag_f32_e32 v148, v0
	v_cvt_f32_ubyte3_e32 v0, v236
	v_rcp_iflag_f32_e32 v149, v0
	v_cvt_f32_ubyte1_e32 v157, v231
	v_cvt_f32_ubyte0_e32 v156, v231
	v_pk_mul_f32 v[150:151], v[150:151], v[156:157]
	v_cvt_f32_ubyte3_e32 v155, v231
	v_cvt_f32_ubyte2_e32 v154, v231
	v_pk_mul_f32 v[44:45], v[44:45], v[150:151]
	v_cvt_f32_ubyte3_e32 v151, v232
	v_cvt_f32_ubyte2_e32 v150, v232
	v_cvt_f32_ubyte0_e32 v0, v237
	v_pk_mul_f32 v[152:153], v[152:153], v[154:155]
	v_pk_mul_f32 v[148:149], v[148:149], v[150:151]
	v_rcp_iflag_f32_e32 v150, v0
	v_cvt_f32_ubyte1_e32 v0, v237
	v_pk_mul_f32 v[46:47], v[46:47], v[152:153]
	v_cvt_f32_ubyte1_e32 v153, v232
	v_cvt_f32_ubyte0_e32 v152, v232
	v_rcp_iflag_f32_e32 v151, v0
	v_cvt_f32_ubyte2_e32 v0, v237
	v_pk_mul_f32 v[2:3], v[2:3], v[152:153]
	v_rcp_iflag_f32_e32 v152, v0
	v_cvt_f32_ubyte3_e32 v0, v237
	v_rcp_iflag_f32_e32 v153, v0
	v_cvt_f32_ubyte0_e32 v0, v246
	v_pk_mul_f32 v[40:41], v[40:41], v[2:3]
	v_rcp_iflag_f32_e32 v2, v0
	v_cvt_f32_ubyte1_e32 v0, v246
	v_rcp_iflag_f32_e32 v3, v0
	v_cvt_f32_ubyte2_e32 v0, v246
	v_pk_mul_f32 v[42:43], v[42:43], v[148:149]
	v_rcp_iflag_f32_e32 v148, v0
	v_cvt_f32_ubyte3_e32 v0, v246
	v_rcp_iflag_f32_e32 v149, v0
	v_cvt_f32_ubyte1_e32 v157, v233
	v_cvt_f32_ubyte0_e32 v156, v233
	v_pk_mul_f32 v[150:151], v[150:151], v[156:157]
	v_cvt_f32_ubyte0_e32 v0, v247
	v_pk_mul_f32 v[36:37], v[36:37], v[150:151]
	v_cvt_f32_ubyte3_e32 v151, v238
	v_cvt_f32_ubyte2_e32 v150, v238
	v_cvt_f32_ubyte3_e32 v155, v233
	v_cvt_f32_ubyte2_e32 v154, v233
	v_pk_mul_f32 v[148:149], v[148:149], v[150:151]
	v_rcp_iflag_f32_e32 v150, v0
	v_cvt_f32_ubyte1_e32 v0, v247
	v_pk_mul_f32 v[152:153], v[152:153], v[154:155]
	v_rcp_iflag_f32_e32 v151, v0
	v_cvt_f32_ubyte2_e32 v0, v247
	v_pk_mul_f32 v[38:39], v[38:39], v[152:153]
	v_cvt_f32_ubyte1_e32 v153, v238
	v_cvt_f32_ubyte0_e32 v152, v238
	v_rcp_iflag_f32_e32 v144, v0
	v_cvt_f32_ubyte3_e32 v0, v247
	v_pk_mul_f32 v[2:3], v[2:3], v[152:153]
	v_rcp_iflag_f32_e32 v145, v0
	v_cvt_f32_ubyte0_e32 v0, v248
	v_cvt_f32_ubyte1_e32 v155, v239
	v_cvt_f32_ubyte0_e32 v154, v239
	v_pk_mul_f32 v[32:33], v[32:33], v[2:3]
	v_rcp_iflag_f32_e32 v2, v0
	v_cvt_f32_ubyte1_e32 v0, v248
	v_cvt_f32_ubyte3_e32 v153, v239
	v_cvt_f32_ubyte2_e32 v152, v239
	v_pk_mul_f32 v[140:141], v[150:151], v[154:155]
	v_rcp_iflag_f32_e32 v3, v0
	v_cvt_f32_ubyte2_e32 v0, v248
	v_pk_mul_f32 v[28:29], v[28:29], v[140:141]
	v_rcp_iflag_f32_e32 v140, v0
	v_cvt_f32_ubyte3_e32 v0, v248
	v_rcp_iflag_f32_e32 v141, v0
	v_pk_mul_f32 v[144:145], v[144:145], v[152:153]
	v_cvt_f32_ubyte0_e32 v0, v249
	v_pk_mul_f32 v[30:31], v[30:31], v[144:145]
	v_cvt_f32_ubyte3_e32 v145, v240
	v_cvt_f32_ubyte2_e32 v144, v240
	v_pk_mul_f32 v[140:141], v[140:141], v[144:145]
	v_rcp_iflag_f32_e32 v144, v0
	v_cvt_f32_ubyte1_e32 v0, v249
	v_rcp_iflag_f32_e32 v145, v0
	v_cvt_f32_ubyte2_e32 v0, v249
	v_pk_mul_f32 v[34:35], v[34:35], v[148:149]
	v_cvt_f32_ubyte1_e32 v149, v240
	v_cvt_f32_ubyte0_e32 v148, v240
	v_rcp_iflag_f32_e32 v146, v0
	v_cvt_f32_ubyte3_e32 v0, v249
	v_pk_mul_f32 v[2:3], v[2:3], v[148:149]
	v_rcp_iflag_f32_e32 v147, v0
	v_cvt_f32_ubyte0_e32 v0, v250
	v_pk_mul_f32 v[24:25], v[24:25], v[2:3]
	v_rcp_iflag_f32_e32 v2, v0
	v_cvt_f32_ubyte1_e32 v0, v250
	v_rcp_iflag_f32_e32 v3, v0
	v_cvt_f32_ubyte2_e32 v0, v250
	v_pk_mul_f32 v[26:27], v[26:27], v[140:141]
	v_rcp_iflag_f32_e32 v140, v0
	v_cvt_f32_ubyte3_e32 v0, v250
	v_rcp_iflag_f32_e32 v141, v0
	v_cvt_f32_ubyte1_e32 v151, v241
	v_cvt_f32_ubyte0_e32 v150, v241
	v_cvt_f32_ubyte3_e32 v149, v241
	v_cvt_f32_ubyte2_e32 v148, v241
	v_pk_mul_f32 v[142:143], v[144:145], v[150:151]
	v_cvt_f32_ubyte0_e32 v0, v251
	v_pk_mul_f32 v[20:21], v[20:21], v[142:143]
	v_cvt_f32_ubyte3_e32 v143, v242
	v_cvt_f32_ubyte2_e32 v142, v242
	v_pk_mul_f32 v[140:141], v[140:141], v[142:143]
	v_rcp_iflag_f32_e32 v142, v0
	v_cvt_f32_ubyte1_e32 v0, v251
	v_pk_mul_f32 v[144:145], v[146:147], v[148:149]
	v_rcp_iflag_f32_e32 v143, v0
	v_cvt_f32_ubyte2_e32 v0, v251
	v_pk_mul_f32 v[22:23], v[22:23], v[144:145]
	v_cvt_f32_ubyte1_e32 v145, v242
	v_cvt_f32_ubyte0_e32 v144, v242
	v_rcp_iflag_f32_e32 v136, v0
	v_cvt_f32_ubyte3_e32 v0, v251
	v_pk_mul_f32 v[2:3], v[2:3], v[144:145]
	v_rcp_iflag_f32_e32 v137, v0
	v_cvt_f32_ubyte0_e32 v0, v252
	v_cvt_f32_ubyte1_e32 v147, v243
	v_cvt_f32_ubyte0_e32 v146, v243
	v_pk_mul_f32 v[16:17], v[16:17], v[2:3]
	v_rcp_iflag_f32_e32 v2, v0
	v_cvt_f32_ubyte1_e32 v0, v252
	v_cvt_f32_ubyte3_e32 v145, v243
	v_cvt_f32_ubyte2_e32 v144, v243
	v_pk_mul_f32 v[132:133], v[142:143], v[146:147]
	v_rcp_iflag_f32_e32 v3, v0
	v_cvt_f32_ubyte2_e32 v0, v252
	v_pk_mul_f32 v[12:13], v[12:13], v[132:133]
	v_rcp_iflag_f32_e32 v132, v0
	v_cvt_f32_ubyte3_e32 v0, v252
	v_rcp_iflag_f32_e32 v133, v0
	v_pk_mul_f32 v[136:137], v[136:137], v[144:145]
	v_cvt_f32_ubyte0_e32 v0, v253
	v_pk_mul_f32 v[14:15], v[14:15], v[136:137]
	v_cvt_f32_ubyte3_e32 v137, v244
	v_cvt_f32_ubyte2_e32 v136, v244
	v_pk_mul_f32 v[132:133], v[132:133], v[136:137]
	v_rcp_iflag_f32_e32 v136, v0
	v_cvt_f32_ubyte1_e32 v0, v253
	v_rcp_iflag_f32_e32 v137, v0
	v_cvt_f32_ubyte2_e32 v0, v253
	v_rcp_iflag_f32_e32 v138, v0
	v_cvt_f32_ubyte3_e32 v0, v253
	v_rcp_iflag_f32_e32 v184, v184
	v_rcp_iflag_f32_e32 v185, v185
	v_rcp_iflag_f32_e32 v188, v188
	v_rcp_iflag_f32_e32 v189, v189
	v_rcp_iflag_f32_e32 v139, v0
	v_pk_mul_f32 v[18:19], v[18:19], v[140:141]
	v_cvt_f32_ubyte1_e32 v141, v244
	v_cvt_f32_ubyte0_e32 v140, v244
	v_pk_mul_f32 v[2:3], v[2:3], v[140:141]
	v_cvt_f32_ubyte3_e32 v141, v245
	v_cvt_f32_ubyte2_e32 v140, v245
	v_cvt_f32_ubyte1_e32 v143, v245
	v_cvt_f32_ubyte0_e32 v142, v245
	v_pk_mul_f32 v[172:173], v[184:185], v[172:173]
	v_pk_mul_f32 v[174:175], v[188:189], v[174:175]
	v_pk_mul_f32 v[134:135], v[136:137], v[142:143]
	v_pk_mul_f32 v[136:137], v[138:139], v[140:141]
	v_pk_mul_f32 v[120:121], v[120:121], v[172:173]
	v_pk_mul_f32 v[116:117], v[116:117], v[174:175]
	v_pk_mul_f32 v[10:11], v[10:11], v[132:133]
	v_pk_mul_f32 v[8:9], v[8:9], v[2:3]
	v_pk_mul_f32 v[6:7], v[6:7], v[136:137]
	v_pk_mul_f32 v[4:5], v[4:5], v[134:135]
